# baseline (speedup 1.0000x reference)
; #define A64_GLOAD(t) do { A64_IDX(); const char* Kt = (const char*)(Kg + (size_t)(t) * 64 * ldk); const char* Vt = (const char*)(Vg + (size_t)(t) * 64 * ldv); \
;         kreg0 = *(const u32x4*)(Kt + (unsigned)(kk0 * ldk + kc0 * 8) * 2u); if (k2) kreg1 = *(const u32x4*)(Kt + (unsigned)(kk1 * ldk + kc1 * 8) * 2u); vreg = *(const u32x4*)(Vt + (unsigned)(vk * ldv + vc * 8) * 2u); } while (0)
; #define A64_LWRITE(bo) do { A64_IDX(); *(LAS u32x4*)(lds + (bo) + kk0 * KP + kc0 * 16) = kreg0; if (k2) *(LAS u32x4*)(lds + (bo) + kk1 * KP + kc1 * 16) = kreg1; \
;         *(LAS u32x4*)(lds + (bo) + KBYTES + (vc >> 2) * 4096 + vk * 64 + (vc & 3) * 16) = vreg; } while (0)
; #define A64_KREAD(bo, half) do { _Pragma("unroll") for (int ds = 0; ds < NDS; ++ds) kf[ds] = *(const LAS bf16x8*)(lds + (bo) + kfr + (half) * 32 * KP + ds * 32); } while (0)
; #define A64_S(dst, q) do { _Pragma("unroll") for (int i = 0; i < 16; ++i) dst[i] = 0.f; _Pragma("unroll") for (int ds = 0; ds < NDS; ++ds) dst = __builtin_amdgcn_mfma_f32_32x32x16_bf16(kf[ds], q[ds], dst, 0, 0, 0); } while (0)
; #define A64_EXP(s, l0, l1, p) do { _Pragma("unroll") for (int i = 0; i < 16; i += 2) { s[i] = __builtin_amdgcn_exp2f(s[i]); s[i + 1] = __builtin_amdgcn_exp2f(s[i + 1]); l0 += s[i]; l1 += s[i + 1]; } \
;         p[0] = pack8(s, 0); p[1] = pack8(s, 1); } while (0)
; #define A64_SB() __builtin_amdgcn_sched_barrier(0)
; template <int DQK>
; __device__ __forceinline__ void attn_unit64p(LAS char* lds, const bf16x8 (&qa)[DQK / 16], const bf16x8 (&qb)[DQK / 16],
;                                              const bf16_t* Kg, int ldk, const bf16_t* Vg, int ldv, int nt, bf16_t* Obase, int ldo, int ogb_off) {
;     ...
;     A64_GLOAD(0); A64_LWRITE(0);
;     __syncthreads();
;     if (nt > 1) A64_GLOAD(1);
;     A64_KREAD(0, 0);
; #pragma nounroll
;     for (int j = 0; j < 2 * nt; ++j) {
;         const int t = j >> 1, hf = j & 1;
;         const unsigned bo = (t & 1) * BUF, bn = ((t & 1) ^ 1) * BUF;
;         const unsigned vo = bo + hf * 2048;
;         const unsigned ko = hf ? bn : bo + 32 * KP;
;         A64_SB(); A64_S(sa, qa); A64_EXP(sb, lb0, lb1, pb);
;         A64_SB(); A64_PV(ob0, ob1, pb);
;         A64_SB(); A64_S(sb, qb); A64_EXP(sa, la0, la1, pa); A64_VREAD(vo, 0);
;         A64_SB(); A64_KREAD(ko, 0); A64_PV(oa0, oa1, pa);
.Lp11_g1_pro:
	s_mov_b32 s24, 0x2000
	s_mov_b32 s25, 0
	v_lshl_add_u64 v[180:181], v[168:169], 0, s[24:25]
	global_load_dwordx4 v[104:107], v[180:181], off
	v_mov_b32_e32 v68, 0xf149f2ca
	v_mov_b32_e32 v69, v68
	v_mov_b32_e32 v70, v68
	v_mov_b32_e32 v71, v68
	v_mov_b32_e32 v72, v68
	v_mov_b32_e32 v73, v68
	v_mov_b32_e32 v74, v68
	v_mov_b32_e32 v75, v68
	v_mov_b32_e32 v76, v68
	v_mov_b32_e32 v77, v68
	v_mov_b32_e32 v78, v68
	v_mov_b32_e32 v79, v68
	v_mov_b32_e32 v64, 0
	v_mov_b32_e32 v65, 0
	v_mov_b32_e32 v66, 0
	v_mov_b32_e32 v67, 0
	v_mov_b32_e32 v230, 0
	v_mov_b32_e32 v231, 0
	v_mov_b32_e32 v214, 0
	v_mov_b32_e32 v215, 0
	v_mov_b32_e32 v216, 0
	v_mov_b32_e32 v217, 0
	v_mov_b32_e32 v218, 0
	v_mov_b32_e32 v219, 0
	v_mov_b32_e32 v220, 0
	v_mov_b32_e32 v221, 0
	v_mov_b32_e32 v248, 0
	v_mov_b32_e32 v249, 0
	v_mov_b32_e32 v250, 0
	v_mov_b32_e32 v251, 0
	v_mov_b32_e32 v252, 0
	v_mov_b32_e32 v253, 0
	v_mov_b32_e32 v254, 0
	v_mov_b32_e32 v255, 0
	s_cmp_eq_u64 s[0:1], 0
	s_cbranch_scc1 .Lp11_noprio
	s_setprio 1
.Lp11_noprio:
.Lp11_loop:
	s_waitcnt lgkmcnt(0)
	v_mfma_f32_32x32x16_bf16 v[80:95], v[182:185], v[128:131], 0
	v_exp_f32_e32 v68, v68
	v_add_f32_e32 v172, v172, v64
	v_exp_f32_e32 v69, v69
	v_add_f32_e32 v173, v173, v65
	v_mfma_f32_32x32x16_bf16 v[80:95], v[186:189], v[124:127], v[80:95]
	v_exp_f32_e32 v70, v70
	v_cvt_pk_bf16_f32 v232, v68, v69
	v_exp_f32_e32 v71, v71
	v_add_f32_e32 v172, v172, v66
	v_mfma_f32_32x32x16_bf16 v[80:95], v[190:193], v[120:123], v[80:95]
	v_exp_f32_e32 v72, v72
	v_cvt_pk_bf16_f32 v233, v70, v71
	v_exp_f32_e32 v73, v73
	v_add_f32_e32 v173, v173, v67
	v_mfma_f32_32x32x16_bf16 v[80:95], v[194:197], v[116:119], v[80:95]
	v_exp_f32_e32 v74, v74
	v_cvt_pk_bf16_f32 v234, v72, v73
	v_exp_f32_e32 v75, v75
	v_add_f32_e32 v172, v172, v68
	v_mfma_f32_32x32x16_bf16 v[80:95], v[198:201], v[108:111], v[80:95]
	v_exp_f32_e32 v76, v76
	v_cvt_pk_bf16_f32 v235, v74, v75
	v_exp_f32_e32 v77, v77
	v_add_f32_e32 v173, v173, v69
	v_mfma_f32_32x32x16_bf16 v[80:95], v[202:205], v[112:115], v[80:95]
	v_exp_f32_e32 v78, v78
	v_cvt_pk_bf16_f32 v236, v76, v77
	v_exp_f32_e32 v79, v79
	v_add_f32_e32 v172, v172, v70
	v_mfma_f32_32x32x16_bf16 v[16:31], v[248:251], v[230:233], v[16:31]
	ds_read_b64_tr_b16 v[248:249], v239 offset:13312
	ds_read_b64_tr_b16 v[250:251], v239 offset:13824
	v_cvt_pk_bf16_f32 v237, v78, v79
	v_add_f32_e32 v173, v173, v71
	v_add_f32_e32 v172, v172, v72
	v_add_f32_e32 v173, v173, v73
	v_mfma_f32_32x32x16_bf16 v[0:15], v[252:255], v[230:233], v[0:15]
	ds_read_b64_tr_b16 v[252:253], v239 offset:17408
	ds_read_b64_tr_b16 v[254:255], v239 offset:17920
	v_add_f32_e32 v172, v172, v74
	v_exp_f32_e32 v80, v80
	v_add_f32_e32 v173, v173, v75
	v_exp_f32_e32 v81, v81
	v_mfma_f32_32x32x16_bf16 v[16:31], v[214:217], v[234:237], v[16:31]
	ds_read_b64_tr_b16 v[214:215], v239 offset:14336
	ds_read_b64_tr_b16 v[216:217], v239 offset:14848
	v_add_f32_e32 v172, v172, v76
	v_exp_f32_e32 v82, v82
	v_add_f32_e32 v173, v173, v77
	v_cvt_pk_bf16_f32 v222, v80, v81
	v_mfma_f32_32x32x16_bf16 v[0:15], v[218:221], v[234:237], v[0:15]
	ds_read_b64_tr_b16 v[218:219], v239 offset:18432
	ds_read_b64_tr_b16 v[220:221], v239 offset:18944
	v_exp_f32_e32 v83, v83
	v_add_f32_e32 v172, v172, v78
	v_add_f32_e32 v173, v173, v79
	v_cvt_pk_bf16_f32 v223, v82, v83
	v_mfma_f32_32x32x16_bf16 v[64:79], v[182:185], v[132:135], 0
	ds_read_b128 v[182:185], v238 offset:6656
	v_exp_f32_e32 v84, v84
	v_add_f32_e32 v170, v170, v80
	v_exp_f32_e32 v85, v85
	v_add_f32_e32 v171, v171, v81
	v_mfma_f32_32x32x16_bf16 v[64:79], v[186:189], v[136:139], v[64:79]
	ds_read_b128 v[186:189], v238 offset:6688
	v_exp_f32_e32 v86, v86
	v_cvt_pk_bf16_f32 v224, v84, v85
	v_exp_f32_e32 v87, v87
	v_add_f32_e32 v170, v170, v82
	v_mfma_f32_32x32x16_bf16 v[64:79], v[190:193], v[140:143], v[64:79]
	ds_read_b128 v[190:193], v238 offset:6720
	v_exp_f32_e32 v88, v88
	v_cvt_pk_bf16_f32 v225, v86, v87
	v_exp_f32_e32 v89, v89
	v_add_f32_e32 v171, v171, v83
	v_mfma_f32_32x32x16_bf16 v[64:79], v[194:197], v[144:147], v[64:79]
	ds_read_b128 v[194:197], v238 offset:6752
	v_exp_f32_e32 v90, v90
	v_cvt_pk_bf16_f32 v226, v88, v89
	v_exp_f32_e32 v91, v91
	v_add_f32_e32 v170, v170, v84
	v_mfma_f32_32x32x16_bf16 v[64:79], v[198:201], v[148:151], v[64:79]
	ds_read_b128 v[198:201], v238 offset:6784
	v_exp_f32_e32 v92, v92
	v_cvt_pk_bf16_f32 v227, v90, v91
	v_exp_f32_e32 v93, v93
	v_add_f32_e32 v171, v171, v85
	v_mfma_f32_32x32x16_bf16 v[64:79], v[202:205], v[152:155], v[64:79]
	ds_read_b128 v[202:205], v238 offset:6816
	v_exp_f32_e32 v94, v94
	v_cvt_pk_bf16_f32 v228, v92, v93
	v_exp_f32_e32 v95, v95
	v_add_f32_e32 v170, v170, v86
	s_waitcnt lgkmcnt(6)
	v_mfma_f32_32x32x16_bf16 v[32:47], v[248:251], v[222:225], v[32:47]
	v_cvt_pk_bf16_f32 v229, v94, v95
	v_add_f32_e32 v171, v171, v87
	v_add_f32_e32 v170, v170, v88
	v_add_f32_e32 v171, v171, v89
	s_waitcnt vmcnt(0)
	ds_write_b128 v159, v[96:99] offset:21504
	s_cmp_eq_u64 s[0:1], 0
	v_mfma_f32_32x32x16_bf16 v[48:63], v[252:255], v[222:225], v[48:63]
	v_add_f32_e32 v170, v170, v90
	v_exp_f32_e32 v64, v64
	v_add_f32_e32 v171, v171, v91
	v_exp_f32_e32 v65, v65
	s_cbranch_scc1 .Lp11_w1_a0
	ds_write_b128 v212, v[100:103] offset:21504

; #define A64_EXP(s, l0, l1, p) do { _Pragma("unroll") for (int i = 0; i < 16; i += 2) { s[i] = __builtin_amdgcn_exp2f(s[i]); s[i + 1] = __builtin_amdgcn_exp2f(s[i + 1]); l0 += s[i]; l1 += s[i + 1]; } \
;         p[0] = pack8(s, 0); p[1] = pack8(s, 1); } while (0)
; #define A64_PV(o0, o1, p) do { o0 = __builtin_amdgcn_mfma_f32_32x32x16_bf16(vf[0], p[0], o0, 0, 0, 0); o1 = __builtin_amdgcn_mfma_f32_32x32x16_bf16(vf[2], p[0], o1, 0, 0, 0); \
;         o0 = __builtin_amdgcn_mfma_f32_32x32x16_bf16(vf[1], p[1], o0, 0, 0, 0); o1 = __builtin_amdgcn_mfma_f32_32x32x16_bf16(vf[3], p[1], o1, 0, 0, 0); } while (0)
; #define A64_SB() __builtin_amdgcn_sched_barrier(0)
; template <int DQK>
; __device__ __forceinline__ void attn_unit64p(LAS char* lds, const bf16x8 (&qa)[DQK / 16], const bf16x8 (&qb)[DQK / 16],
;                                              const bf16_t* Kg, int ldk, const bf16_t* Vg, int ldv, int nt, bf16_t* Obase, int ldo, int ogb_off) {
;     ...
;     A64_SB(); A64_EXP(sb, lb0, lb1, pb); A64_PV(ob0, ob1, pb);
;     __syncthreads();
.Lp11_drain:
	s_setprio 0
	v_exp_f32_e32 v68, v68
	v_add_f32_e32 v172, v172, v64
	v_exp_f32_e32 v69, v69
	v_add_f32_e32 v173, v173, v65
	v_exp_f32_e32 v70, v70
	v_cvt_pk_bf16_f32 v232, v68, v69
	v_exp_f32_e32 v71, v71
	v_add_f32_e32 v172, v172, v66
	v_exp_f32_e32 v72, v72
	v_cvt_pk_bf16_f32 v233, v70, v71
	v_exp_f32_e32 v73, v73
	v_add_f32_e32 v173, v173, v67
	v_exp_f32_e32 v74, v74
	v_cvt_pk_bf16_f32 v234, v72, v73
	v_exp_f32_e32 v75, v75
	v_add_f32_e32 v172, v172, v68
	v_exp_f32_e32 v76, v76
	v_cvt_pk_bf16_f32 v235, v74, v75
	v_exp_f32_e32 v77, v77
	v_add_f32_e32 v173, v173, v69
	v_exp_f32_e32 v78, v78
	v_cvt_pk_bf16_f32 v236, v76, v77
	v_exp_f32_e32 v79, v79
	v_add_f32_e32 v172, v172, v70
	v_cvt_pk_bf16_f32 v237, v78, v79
	v_add_f32_e32 v173, v173, v71
	v_add_f32_e32 v172, v172, v72
	v_add_f32_e32 v173, v173, v73
	v_add_f32_e32 v172, v172, v74
	v_add_f32_e32 v173, v173, v75
	v_add_f32_e32 v172, v172, v76
	v_add_f32_e32 v173, v173, v77
	v_add_f32_e32 v172, v172, v78
	v_add_f32_e32 v173, v173, v79
	s_nop 1
	v_mfma_f32_32x32x16_bf16 v[16:31], v[248:251], v[230:233], v[16:31]
	v_mfma_f32_32x32x16_bf16 v[0:15], v[252:255], v[230:233], v[0:15]
	v_mfma_f32_32x32x16_bf16 v[16:31], v[214:217], v[234:237], v[16:31]
	v_mfma_f32_32x32x16_bf16 v[0:15], v[218:221], v[234:237], v[0:15]
	s_waitcnt vmcnt(0)
	s_waitcnt lgkmcnt(0)
	s_barrier
	s_branch .LBB0_1115
